# ret_out epilogue: the wait right after the batched gate/gain loads waits only lgkmcnt (first gate fragment is already in registers); the batch is drained at the first consumer
# speedup vs baseline: 1.0073x; 1.0073x over previous
.LBB0_490:
	s_or_b64 exec, exec, s[0:1]
	v_lshlrev_b32_e32 v70, 7, v6
	v_lshlrev_b32_e32 v2, 3, v5
	v_ashrrev_i32_e32 v71, 31, v70
	v_and_b32_e32 v7, 56, v2
	v_bfe_u32 v13, v5, 3, 5
	v_lshlrev_b64 v[72:73], 1, v[70:71]
	v_lshlrev_b32_e32 v0, 3, v7
	v_mov_b32_e32 v1, v65
	v_or_b32_e32 v8, v3, v13
	v_lshl_add_u64 v[0:1], s[40:41], 0, v[0:1]
	v_lshlrev_b32_e32 v8, 9, v8
	v_mov_b32_e32 v9, v65
	v_lshl_add_u64 v[18:19], s[38:39], 0, v[72:73]
	v_lshlrev_b32_e32 v64, 1, v7
	v_lshl_add_u64 v[38:39], v[0:1], 0, v[8:9]
	v_lshl_add_u64 v[42:43], v[18:19], 0, v[64:65]
	v_add_u32_e32 v7, v68, v13
	global_load_dwordx4 v[8:11], v[38:39], off
	global_load_dwordx4 v[14:17], v[38:39], off offset:16
	global_load_dwordx4 v[18:21], v[38:39], off offset:32
	v_mad_i64_i32 v[34:35], s[0:1], v7, s57, v[42:43]
	global_load_dwordx4 v[22:25], v[34:35], off
	global_load_dwordx4 v[26:29], v[34:35], off offset:128
	global_load_dwordx4 v[30:33], v[34:35], off offset:1536
	s_nop 0
	global_load_dwordx4 v[34:37], v[34:35], off offset:1664
	s_nop 0
	global_load_dwordx4 v[38:41], v[38:39], off offset:48
	v_or_b32_sdwa v140, v5, s61 dst_sel:DWORD dst_unused:UNUSED_PAD src0_sel:BYTE_0 src1_sel:DWORD
	v_lshrrev_b32_e32 v141, 3, v140
	v_add_u32_e32 v142, v68, v141
	v_mad_i64_i32 v[134:135], s[0:1], v142, s57, v[42:43]
	v_or_b32_e32 v143, v3, v141
	v_lshlrev_b32_e32 v136, 9, v143
	v_mov_b32_e32 v137, v65
	v_lshl_add_u64 v[136:137], v[0:1], 0, v[136:137]
	global_load_dwordx4 v[160:163], v[134:135], off
	global_load_dwordx4 v[164:167], v[134:135], off offset:128
	global_load_dwordx4 v[168:171], v[134:135], off offset:1536
	global_load_dwordx4 v[172:175], v[134:135], off offset:1664
	global_load_dwordx4 v[176:179], v[136:137], off
	global_load_dwordx4 v[180:183], v[136:137], off offset:16
	global_load_dwordx4 v[184:187], v[136:137], off offset:32
	global_load_dwordx4 v[188:191], v[136:137], off offset:48
	v_bfe_u32 v140, v5, 4, 4
	v_add_u32_e32 v140, v68, v140
	v_mad_i64_i32 v[138:139], s[0:1], v140, s57, v[66:67]
	v_lshl_add_u64 v[138:139], v[138:139], 0, v[72:73]
	v_lshlrev_b32_e32 v140, 3, v5
	v_and_b32_e32 v140, 0x78, v140
	v_lshlrev_b32_e32 v140, 1, v140
	v_mov_b32_e32 v141, v65
	v_lshl_add_u64 v[138:139], v[138:139], 0, v[140:141]
	v_mov_b32_e32 v140, 0x1a000
	global_load_dwordx4 v[192:195], v[138:139], off offset:3072
	v_lshl_add_u64 v[138:139], v[138:139], 0, v[140:141]
	global_load_dwordx4 v[196:199], v[138:139], off offset:3072
	v_lshl_add_u64 v[138:139], v[138:139], 0, v[140:141]
	global_load_dwordx4 v[200:203], v[138:139], off offset:3072
	v_lshl_add_u64 v[138:139], v[138:139], 0, v[140:141]
	global_load_dwordx4 v[204:207], v[138:139], off offset:3072
	v_mul_u32_u24_e32 v7, 0x88, v13
	v_mad_i32_i24 v4, v4, s52, 0
	v_lshlrev_b32_e32 v7, 1, v7
	v_add3_u32 v7, v4, v7, v64
	s_add_i32 s2, s2, s84
	s_waitcnt vmcnt(12) lgkmcnt(0)
	v_mov_b32_e32 v44, v8
	v_mov_b32_e32 v45, v10
	v_mov_b32_e32 v10, v9
	v_mov_b32_e32 v8, v14
	v_mov_b32_e32 v9, v16
	v_mov_b32_e32 v16, v15
	v_mov_b32_e32 v14, v18
	v_mov_b32_e32 v15, v20
	v_mov_b32_e32 v20, v19
	v_lshlrev_b32_e32 v18, 16, v22
	v_and_b32_e32 v19, 0xffff0000, v22
	v_lshlrev_b32_e32 v22, 16, v23
	v_and_b32_e32 v23, 0xffff0000, v23
	v_lshlrev_b32_e32 v48, 16, v26
	v_and_b32_e32 v49, 0xffff0000, v26
	v_lshlrev_b32_e32 v26, 16, v27
	v_and_b32_e32 v27, 0xffff0000, v27
	v_lshlrev_b32_e32 v52, 16, v30
	v_and_b32_e32 v53, 0xffff0000, v30
	v_lshlrev_b32_e32 v30, 16, v31
	v_and_b32_e32 v31, 0xffff0000, v31
	v_lshlrev_b32_e32 v56, 16, v34
	v_and_b32_e32 v57, 0xffff0000, v34
	v_lshlrev_b32_e32 v34, 16, v35
	v_and_b32_e32 v35, 0xffff0000, v35
	v_pk_mul_f32 v[76:77], v[16:17], v[26:27]
	v_pk_mul_f32 v[84:85], v[16:17], v[22:23]
	v_pk_mul_f32 v[86:87], v[16:17], v[34:35]
	v_pk_mul_f32 v[16:17], v[16:17], v[30:31]
	v_lshlrev_b32_e32 v46, 16, v24
	v_and_b32_e32 v47, 0xffff0000, v24
	v_lshlrev_b32_e32 v50, 16, v28
	v_and_b32_e32 v51, 0xffff0000, v28
	v_pk_mul_f32 v[60:61], v[10:11], v[48:49]
	v_pk_mul_f32 v[62:63], v[10:11], v[18:19]
	v_pk_mul_f32 v[74:75], v[10:11], v[56:57]
	v_pk_mul_f32 v[10:11], v[10:11], v[52:53]
	v_pk_fma_f32 v[22:23], v[8:9], v[22:23], v[76:77] neg_lo:[0,0,1] neg_hi:[0,0,1]
	v_pk_fma_f32 v[26:27], v[8:9], v[26:27], v[84:85]
	v_pk_fma_f32 v[30:31], v[8:9], v[30:31], v[86:87] neg_lo:[0,0,1] neg_hi:[0,0,1]
	v_pk_fma_f32 v[8:9], v[8:9], v[34:35], v[16:17]
	v_lshlrev_b32_e32 v58, 16, v36
	v_and_b32_e32 v59, 0xffff0000, v36
	v_pk_mul_f32 v[88:89], v[20:21], v[50:51]
	v_pk_fma_f32 v[18:19], v[44:45], v[18:19], v[60:61] neg_lo:[0,0,1] neg_hi:[0,0,1]
	v_pk_fma_f32 v[48:49], v[44:45], v[48:49], v[62:63]
	v_pk_fma_f32 v[52:53], v[44:45], v[52:53], v[74:75] neg_lo:[0,0,1] neg_hi:[0,0,1]
	v_pk_fma_f32 v[10:11], v[44:45], v[56:57], v[10:11]
	v_pk_mul_f32 v[44:45], v[8:9], s[44:45] op_sel_hi:[1,0]
	v_pk_mul_f32 v[8:9], v[20:21], v[46:47]
	v_lshlrev_b32_e32 v54, 16, v32
	v_and_b32_e32 v55, 0xffff0000, v32
	v_pk_mul_f32 v[34:35], v[10:11], s[44:45] op_sel_hi:[1,0]
	v_pk_fma_f32 v[10:11], v[14:15], v[46:47], v[88:89] neg_lo:[0,0,1] neg_hi:[0,0,1]
	v_pk_fma_f32 v[46:47], v[14:15], v[50:51], v[8:9]
	v_pk_mul_f32 v[8:9], v[20:21], v[58:59]
	v_lshlrev_b32_e32 v28, 16, v29
	v_pk_fma_f32 v[8:9], v[14:15], v[54:55], v[8:9] neg_lo:[0,0,1] neg_hi:[0,0,1]
	v_and_b32_e32 v29, 0xffff0000, v29
	v_pk_mul_f32 v[50:51], v[8:9], s[44:45] op_sel_hi:[1,0]
	v_pk_mul_f32 v[8:9], v[20:21], v[54:55]
	v_lshlrev_b32_e32 v24, 16, v25
	v_pk_fma_f32 v[8:9], v[14:15], v[58:59], v[8:9]
	v_and_b32_e32 v25, 0xffff0000, v25
	v_pk_mul_f32 v[14:15], v[8:9], s[44:45] op_sel_hi:[1,0]
	v_mov_b32_e32 v9, v40
	v_mov_b32_e32 v40, v39
	v_mov_b32_e32 v8, v38
	v_pk_mul_f32 v[20:21], v[40:41], v[28:29]
	v_lshlrev_b32_e32 v36, 16, v37
	v_and_b32_e32 v37, 0xffff0000, v37
	v_pk_fma_f32 v[20:21], v[8:9], v[24:25], v[20:21] neg_lo:[0,0,1] neg_hi:[0,0,1]
	v_pk_mul_f32 v[24:25], v[40:41], v[24:25]
	v_lshlrev_b32_e32 v32, 16, v33
	v_and_b32_e32 v33, 0xffff0000, v33
	v_pk_fma_f32 v[24:25], v[8:9], v[28:29], v[24:25]
	v_pk_mul_f32 v[28:29], v[40:41], v[36:37]
	v_cvt_pk_bf16_f32 v10, v10, v11
	v_pk_fma_f32 v[28:29], v[8:9], v[32:33], v[28:29] neg_lo:[0,0,1] neg_hi:[0,0,1]
	v_pk_mul_f32 v[32:33], v[40:41], v[32:33]
	v_cvt_pk_bf16_f32 v11, v20, v21
	v_pk_fma_f32 v[8:9], v[8:9], v[36:37], v[32:33]
	v_pk_mul_f32 v[16:17], v[52:53], s[44:45] op_sel_hi:[1,0]
	v_pk_mul_f32 v[32:33], v[8:9], s[44:45] op_sel_hi:[1,0]
	v_cvt_pk_bf16_f32 v8, v18, v19
	v_cvt_pk_bf16_f32 v9, v22, v23
	v_pk_mul_f32 v[30:31], v[30:31], s[44:45] op_sel_hi:[1,0]
	v_pk_mul_f32 v[28:29], v[28:29], s[44:45] op_sel_hi:[1,0]
	ds_write_b128 v7, v[8:11]
	v_cvt_pk_bf16_f32 v8, v48, v49
	v_cvt_pk_bf16_f32 v9, v26, v27
	v_cvt_pk_bf16_f32 v10, v46, v47
	v_cvt_pk_bf16_f32 v11, v24, v25
	ds_write_b128 v7, v[8:11] offset:128
	v_cvt_pk_bf16_f32 v8, v16, v17
	v_cvt_pk_bf16_f32 v9, v30, v31
	v_cvt_pk_bf16_f32 v10, v50, v51
	v_cvt_pk_bf16_f32 v11, v28, v29
	ds_write_b128 v7, v[8:11] offset:17408
	v_cvt_pk_bf16_f32 v8, v34, v35
	v_cvt_pk_bf16_f32 v9, v44, v45
	v_cvt_pk_bf16_f32 v10, v14, v15
	v_cvt_pk_bf16_f32 v11, v32, v33
	ds_write_b128 v7, v[8:11] offset:17536
	v_or_b32_sdwa v7, v5, s61 dst_sel:DWORD dst_unused:UNUSED_PAD src0_sel:BYTE_0 src1_sel:DWORD
	v_lshrrev_b32_e32 v13, 3, v7
	v_add_u32_e32 v8, v68, v13
	v_or_b32_e32 v3, v3, v13
	v_mad_i64_i32 v[22:23], s[0:1], v8, s57, v[42:43]
	v_lshlrev_b32_e32 v26, 9, v3
	v_mov_b32_e32 v27, v65
	s_nop 0
	v_lshl_add_u64 v[0:1], v[0:1], 0, v[26:27]
	v_mul_u32_u24_e32 v3, 0x88, v13
	v_lshlrev_b32_e32 v3, 1, v3
	v_add3_u32 v3, v4, v3, v64
	v_lshrrev_b32_e32 v7, 4, v7
	s_waitcnt vmcnt(4) lgkmcnt(0)
	v_mov_b64_e32 v[8:9], v[160:161]
	v_mov_b64_e32 v[10:11], v[162:163]
	v_mov_b64_e32 v[14:15], v[164:165]
	v_mov_b64_e32 v[16:17], v[166:167]
	v_mov_b64_e32 v[18:19], v[168:169]
	v_mov_b64_e32 v[20:21], v[170:171]
	v_mov_b64_e32 v[22:23], v[172:173]
	v_mov_b64_e32 v[24:25], v[174:175]
	v_mov_b64_e32 v[26:27], v[176:177]
	v_mov_b64_e32 v[28:29], v[178:179]
	v_mov_b64_e32 v[30:31], v[180:181]
	v_mov_b64_e32 v[32:33], v[182:183]
	v_mov_b64_e32 v[34:35], v[184:185]
	v_mov_b64_e32 v[36:37], v[186:187]
	v_mov_b64_e32 v[38:39], v[188:189]
	v_mov_b64_e32 v[40:41], v[190:191]
	v_lshlrev_b32_e32 v0, 16, v8
	v_lshlrev_b32_e32 v44, 16, v14
	v_and_b32_e32 v45, 0xffff0000, v14
	v_mov_b32_e32 v57, v28
	v_mov_b32_e32 v28, v27
	v_and_b32_e32 v1, 0xffff0000, v8
	v_mov_b32_e32 v56, v26
	v_pk_mul_f32 v[26:27], v[28:29], v[44:45]
	v_lshlrev_b32_e32 v52, 16, v22
	v_and_b32_e32 v53, 0xffff0000, v22
	v_pk_fma_f32 v[26:27], v[56:57], v[0:1], v[26:27] neg_lo:[0,0,1] neg_hi:[0,0,1]
	v_pk_mul_f32 v[0:1], v[28:29], v[0:1]
	v_lshlrev_b32_e32 v48, 16, v18
	v_and_b32_e32 v49, 0xffff0000, v18
	v_pk_fma_f32 v[0:1], v[56:57], v[44:45], v[0:1]
	v_pk_mul_f32 v[44:45], v[28:29], v[52:53]
	v_lshlrev_b32_e32 v14, 16, v15
	v_and_b32_e32 v15, 0xffff0000, v15
	v_pk_fma_f32 v[44:45], v[56:57], v[48:49], v[44:45] neg_lo:[0,0,1] neg_hi:[0,0,1]
	v_pk_mul_f32 v[28:29], v[28:29], v[48:49]
	v_mov_b32_e32 v49, v32
	v_mov_b32_e32 v32, v31
	v_lshlrev_b32_e32 v8, 16, v9
	v_and_b32_e32 v9, 0xffff0000, v9
	v_mov_b32_e32 v48, v30
	v_pk_mul_f32 v[30:31], v[32:33], v[14:15]
	v_lshlrev_b32_e32 v22, 16, v23
	v_and_b32_e32 v23, 0xffff0000, v23
	v_pk_fma_f32 v[30:31], v[48:49], v[8:9], v[30:31] neg_lo:[0,0,1] neg_hi:[0,0,1]
	v_pk_mul_f32 v[8:9], v[32:33], v[8:9]
	v_lshlrev_b32_e32 v18, 16, v19
	v_and_b32_e32 v19, 0xffff0000, v19
	v_pk_fma_f32 v[14:15], v[48:49], v[14:15], v[8:9]
	v_pk_mul_f32 v[8:9], v[32:33], v[22:23]
	v_pk_fma_f32 v[28:29], v[56:57], v[52:53], v[28:29]
	v_pk_fma_f32 v[8:9], v[48:49], v[18:19], v[8:9] neg_lo:[0,0,1] neg_hi:[0,0,1]
	v_lshlrev_b32_e32 v42, 16, v10
	v_pk_mul_f32 v[52:53], v[8:9], s[44:45] op_sel_hi:[1,0]
	v_pk_mul_f32 v[8:9], v[32:33], v[18:19]
	v_and_b32_e32 v43, 0xffff0000, v10
	v_pk_fma_f32 v[8:9], v[48:49], v[22:23], v[8:9]
	v_lshlrev_b32_e32 v46, 16, v16
	v_and_b32_e32 v47, 0xffff0000, v16
	v_lshlrev_b32_e32 v50, 16, v20
	v_and_b32_e32 v51, 0xffff0000, v20
	v_lshlrev_b32_e32 v54, 16, v24
	v_and_b32_e32 v55, 0xffff0000, v24
	v_pk_mul_f32 v[18:19], v[8:9], s[44:45] op_sel_hi:[1,0]
	v_mov_b32_e32 v9, v36
	v_mov_b32_e32 v36, v35
	v_mov_b32_e32 v8, v34
	v_pk_mul_f32 v[22:23], v[36:37], v[46:47]
	v_pk_mul_f32 v[32:33], v[36:37], v[42:43]
	v_pk_mul_f32 v[34:35], v[36:37], v[54:55]
	v_pk_mul_f32 v[36:37], v[36:37], v[50:51]
	v_pk_fma_f32 v[22:23], v[8:9], v[42:43], v[22:23] neg_lo:[0,0,1] neg_hi:[0,0,1]
	v_pk_fma_f32 v[32:33], v[8:9], v[46:47], v[32:33]
	v_pk_fma_f32 v[34:35], v[8:9], v[50:51], v[34:35] neg_lo:[0,0,1] neg_hi:[0,0,1]
	v_pk_fma_f32 v[8:9], v[8:9], v[54:55], v[36:37]
	v_lshlrev_b32_e32 v16, 16, v17
	v_and_b32_e32 v17, 0xffff0000, v17
	v_pk_mul_f32 v[36:37], v[8:9], s[44:45] op_sel_hi:[1,0]
	v_mov_b32_e32 v9, v40
	v_mov_b32_e32 v40, v39
	v_lshlrev_b32_e32 v10, 16, v11
	v_and_b32_e32 v11, 0xffff0000, v11
	v_mov_b32_e32 v8, v38
	v_pk_mul_f32 v[38:39], v[40:41], v[16:17]
	v_lshlrev_b32_e32 v24, 16, v25
	v_and_b32_e32 v25, 0xffff0000, v25
	v_pk_fma_f32 v[38:39], v[8:9], v[10:11], v[38:39] neg_lo:[0,0,1] neg_hi:[0,0,1]
	v_pk_mul_f32 v[10:11], v[40:41], v[10:11]
	v_lshlrev_b32_e32 v20, 16, v21
	v_and_b32_e32 v21, 0xffff0000, v21
	v_pk_fma_f32 v[16:17], v[8:9], v[16:17], v[10:11]
	v_pk_mul_f32 v[10:11], v[40:41], v[24:25]
	v_pk_mul_f32 v[44:45], v[44:45], s[44:45] op_sel_hi:[1,0]
	v_pk_fma_f32 v[10:11], v[8:9], v[20:21], v[10:11] neg_lo:[0,0,1] neg_hi:[0,0,1]
	v_pk_mul_f32 v[34:35], v[34:35], s[44:45] op_sel_hi:[1,0]
	v_pk_mul_f32 v[42:43], v[10:11], s[44:45] op_sel_hi:[1,0]
	v_pk_mul_f32 v[10:11], v[40:41], v[20:21]
	v_pk_mul_f32 v[28:29], v[28:29], s[44:45] op_sel_hi:[1,0]
	v_pk_fma_f32 v[8:9], v[8:9], v[24:25], v[10:11]
	v_cvt_pk_bf16_f32 v10, v22, v23
	v_pk_mul_f32 v[20:21], v[8:9], s[44:45] op_sel_hi:[1,0]
	v_cvt_pk_bf16_f32 v8, v26, v27
	v_cvt_pk_bf16_f32 v9, v30, v31
	v_cvt_pk_bf16_f32 v11, v38, v39
	ds_write_b128 v3, v[8:11]
	v_cvt_pk_bf16_f32 v8, v0, v1
	v_cvt_pk_bf16_f32 v9, v14, v15
	v_cvt_pk_bf16_f32 v10, v32, v33
	v_cvt_pk_bf16_f32 v11, v16, v17
	ds_write_b128 v3, v[8:11] offset:128
	v_cvt_pk_bf16_f32 v8, v44, v45
	v_cvt_pk_bf16_f32 v9, v52, v53
	v_cvt_pk_bf16_f32 v10, v34, v35
	v_cvt_pk_bf16_f32 v11, v42, v43
	ds_write_b128 v3, v[8:11] offset:17408
	v_cvt_pk_bf16_f32 v8, v28, v29
	v_cvt_pk_bf16_f32 v9, v18, v19
	v_cvt_pk_bf16_f32 v10, v36, v37
	v_cvt_pk_bf16_f32 v11, v20, v21
	ds_write_b128 v3, v[8:11] offset:17536
	v_bfe_u32 v9, v5, 4, 4
	v_add_u32_e32 v10, v68, v9
	v_and_b32_e32 v8, 0x78, v2
	v_mad_i64_i32 v[0:1], s[0:1], v10, s57, v[66:67]
	v_lshl_add_u64 v[0:1], v[0:1], 0, v[72:73]
	v_lshlrev_b32_e32 v64, 1, v8
	v_lshl_add_u64 v[0:1], v[0:1], 0, v[64:65]
	v_mul_u32_u24_e32 v8, 0x48, v8
	v_lshlrev_b32_e32 v11, 1, v8
	v_lshlrev_b32_e32 v9, 1, v9
	v_add_u32_e32 v14, v4, v11
	v_add3_u32 v13, v4, v9, v11
	v_add_u32_e32 v15, v14, v9
	v_add_u32_e32 v8, 32, v10
	v_mad_i64_i32 v[8:9], s[0:1], v8, s57, v[66:67]
	v_lshl_add_u64 v[8:9], v[8:9], 0, v[72:73]
	v_lshl_add_u64 v[8:9], v[8:9], 0, v[64:65]
	v_and_b32_e32 v20, 15, v5
	v_bfe_u32 v21, v5, 4, 2
	v_lshrrev_b32_e32 v5, 2, v5
	v_and_or_b32 v76, v5, 48, v20
	v_lshlrev_b32_e32 v5, 2, v21
	v_lshlrev_b32_e32 v74, 4, v21
	v_sub_u32_e32 v69, v76, v5
	v_add_u32_e32 v16, -2, v69
	v_cvt_f32_i32_e32 v16, v16
	v_add_u32_e32 v17, -3, v69
	v_subrev_u32_e32 v22, 17, v69
	v_subrev_u32_e32 v23, 18, v69
	v_subrev_u32_e32 v24, 19, v69
	v_subrev_u32_e32 v25, 33, v69
	v_cvt_f32_i32_e32 v17, v17
	v_cvt_f32_i32_e32 v22, v22
	v_cvt_f32_i32_e32 v23, v23
	v_cvt_f32_i32_e32 v24, v24
	v_cvt_f32_i32_e32 v25, v25
	v_subrev_u32_e32 v26, 34, v69
	v_subrev_u32_e32 v27, 35, v69
	v_cvt_f32_i32_e32 v26, v26
	v_cvt_f32_i32_e32 v34, v27
	v_subrev_u32_e32 v28, 49, v69
	s_add_i32 s45, s45, s48
	s_cmpk_gt_i32 s2, 0x62f
	s_waitcnt vmcnt(3) lgkmcnt(0)
	v_mov_b64_e32 v[0:1], v[192:193]
	v_mov_b64_e32 v[2:3], v[194:195]
	ds_write_b16 v13, v0 offset:34816
	ds_write_b16_d16_hi v15, v0 offset:34960
	ds_write_b16 v13, v1 offset:35104
	ds_write_b16_d16_hi v15, v1 offset:35248
	ds_write_b16 v13, v2 offset:35392
	ds_write_b16_d16_hi v15, v2 offset:35536
	ds_write_b16 v13, v3 offset:35680
	ds_write_b16_d16_hi v15, v3 offset:35824
	v_add_u32_e32 v0, v68, v7
	v_mad_i64_i32 v[0:1], s[0:1], v0, s57, v[66:67]
	v_lshl_add_u64 v[0:1], v[0:1], 0, v[72:73]
	v_lshl_add_u64 v[0:1], v[0:1], 0, v[64:65]
	v_lshlrev_b32_e32 v7, 1, v7
	v_add3_u32 v11, v4, v7, v11
	v_add_u32_e32 v7, v14, v7
	s_waitcnt vmcnt(2) lgkmcnt(0)
	v_mov_b64_e32 v[0:1], v[196:197]
	v_mov_b64_e32 v[2:3], v[198:199]
	ds_write_b16 v11, v0 offset:34816
	ds_write_b16_d16_hi v7, v0 offset:34960
	ds_write_b16 v11, v1 offset:35104
	ds_write_b16_d16_hi v7, v1 offset:35248
	ds_write_b16 v11, v2 offset:35392
	ds_write_b16_d16_hi v7, v2 offset:35536
	ds_write_b16 v11, v3 offset:35680
	ds_write_b16_d16_hi v7, v3 offset:35824
	v_cvt_f32_i32_e32 v8, v6
	v_add_u32_e32 v6, 48, v10
	v_mad_i64_i32 v[6:7], s[0:1], v6, s57, v[66:67]
	v_lshl_add_u64 v[6:7], v[6:7], 0, v[72:73]
	v_lshl_add_u64 v[6:7], v[6:7], 0, v[64:65]
	s_waitcnt vmcnt(1) lgkmcnt(0)
	v_mov_b64_e32 v[0:1], v[200:201]
	v_mov_b64_e32 v[2:3], v[202:203]
	ds_write_b16 v13, v0 offset:34880
	ds_write_b16_d16_hi v15, v0 offset:35024
	ds_write_b16 v13, v1 offset:35168
	ds_write_b16_d16_hi v15, v1 offset:35312
	ds_write_b16 v13, v2 offset:35456
	ds_write_b16_d16_hi v15, v2 offset:35600
	ds_write_b16 v13, v3 offset:35744
	ds_write_b16_d16_hi v15, v3 offset:35888
	v_sub_f32_e32 v8, 0xc0a00000, v8
	v_cmp_gt_f32_e32 vcc, s53, v8
	v_add_u32_e32 v9, v4, v74
	v_xad_u32 v10, v5, -1, v76
	v_cndmask_b32_e32 v29, 0, v78, vcc
	v_add_f32_e32 v8, v8, v29
	v_exp_f32_e32 v6, v8
	v_cndmask_b32_e32 v7, 0, v79, vcc
	v_mad_u32_u24 v18, v76, s62, v9
	v_mad_u32_u24 v19, v20, s62, v9
	v_ldexp_f32 v6, v6, v7
	v_sub_f32_e32 v6, 1.0, v6
	v_cmp_gt_f32_e32 vcc, s54, v6
	v_cvt_f32_i32_e32 v9, v69
	v_cvt_f32_i32_e32 v10, v10
	v_cndmask_b32_e64 v7, 0, 32, vcc
	v_ldexp_f32 v6, v6, v7
	v_log_f32_e32 v6, v6
	v_cndmask_b32_e32 v7, 0, v80, vcc
	v_or_b32_e32 v14, 32, v5
	s_waitcnt vmcnt(0) lgkmcnt(0)
	v_mov_b64_e32 v[0:1], v[204:205]
	v_mov_b64_e32 v[2:3], v[206:207]
	ds_write_b16 v13, v0 offset:34912
	ds_write_b16_d16_hi v15, v0 offset:35056
	ds_write_b16 v13, v1 offset:35200
	ds_write_b16_d16_hi v15, v1 offset:35344
	ds_write_b16 v13, v2 offset:35488
	ds_write_b16_d16_hi v15, v2 offset:35632
	ds_write_b16 v13, v3 offset:35776
	ds_write_b16_d16_hi v15, v3 offset:35920
	v_mul_f32_e32 v8, 0x3f317217, v6
	v_fma_f32 v8, v6, s55, -v8
	v_fmac_f32_e32 v8, 0x3377d1cf, v6
	v_fmac_f32_e32 v8, 0x3f317217, v6
	v_cmp_lt_f32_e64 vcc, |v6|, s56
	s_waitcnt lgkmcnt(0)
	s_barrier
	v_add_u32_e32 v254, v68, v76
	v_mul_u32_u24_e32 v254, 0x1a00, v254
	v_lshrrev_b32_e32 v253, 1, v74
	v_add3_u32 v254, v254, v72, v253
	v_add_u32_e32 v254, s46, v254
	global_load_dwordx2 v[252:253], v254, s[38:39]
	global_load_dword v149, v254, s[38:39] offset:128
	v_cndmask_b32_e32 v6, v6, v8, vcc
	v_sub_f32_e32 v6, v6, v7
	ds_read_b128 v[0:3], v19 offset:17408
	v_sub_u32_e32 v14, v76, v14
	v_mul_f32_e32 v83, 0x3fb8aa3b, v6
	v_cvt_f32_i32_e32 v14, v14
	v_mul_f32_e64 v6, |v9|, v83
	v_mul_f32_e64 v7, |v10|, v83
	v_mul_f32_e64 v8, |v16|, v83
	v_cmp_gt_f32_e32 vcc, s53, v6
	v_cmp_gt_f32_e64 s[0:1], s53, v7
	v_cmp_gt_f32_e64 s[4:5], s53, v8
	v_or_b32_e32 v11, 16, v5
	v_or_b32_e32 v5, 48, v5
	v_cndmask_b32_e32 v6, 0, v78, vcc
	v_cndmask_b32_e64 v7, 0, v78, s[0:1]
	v_cndmask_b32_e64 v8, 0, v78, s[4:5]
	v_sub_u32_e32 v11, v76, v11
	v_sub_u32_e32 v5, v76, v5
	v_fma_f32 v42, |v9|, v83, v6
	v_fma_f32 v10, |v10|, v83, v7
	v_fma_f32 v43, |v16|, v83, v8
	ds_read_b128 v[56:59], v18
	ds_read_b128 v[6:9], v19 offset:21760
	v_cvt_f32_i32_e32 v11, v11
	v_cvt_f32_i32_e32 v5, v5
	v_mul_f32_e64 v27, |v17|, v83
	v_mul_f32_e64 v29, |v22|, v83
	v_mul_f32_e64 v30, |v23|, v83
	v_mul_f32_e64 v31, |v24|, v83
	v_mul_f32_e64 v32, |v14|, v83
	v_mul_f32_e64 v33, |v25|, v83
	v_cmp_gt_f32_e64 s[6:7], s53, v27
	v_cmp_gt_f32_e64 s[10:11], s53, v29
	v_cmp_gt_f32_e64 s[12:13], s53, v30
	v_cmp_gt_f32_e64 s[14:15], s53, v31
	v_cmp_gt_f32_e64 s[16:17], s53, v32
	v_cmp_gt_f32_e64 s[18:19], s53, v33
	v_cndmask_b32_e64 v27, 0, v78, s[6:7]
	v_cndmask_b32_e64 v29, 0, v78, s[10:11]
	v_cndmask_b32_e64 v30, 0, v78, s[12:13]
	v_cndmask_b32_e64 v31, 0, v78, s[14:15]
	v_cndmask_b32_e64 v32, 0, v78, s[16:17]
	v_cndmask_b32_e64 v33, 0, v78, s[18:19]
	v_fma_f32 v44, |v17|, v83, v27
	v_fma_f32 v45, |v22|, v83, v29
	v_fma_f32 v48, |v23|, v83, v30
	v_fma_f32 v49, |v24|, v83, v31
	v_fma_f32 v50, |v14|, v83, v32
	v_fma_f32 v13, |v25|, v83, v33
	ds_read_b128 v[60:63], v18 offset:64
	ds_read_b128 v[14:17], v19 offset:17472
	ds_read_b128 v[22:25], v19 offset:26112
	s_waitcnt lgkmcnt(4)
	v_mfma_f32_16x16x32_bf16 v[0:3], v[0:3], v[56:59], 0
	v_cvt_f32_i32_e32 v64, v28
	v_mul_f32_e64 v28, |v11|, v83
	v_mul_f32_e64 v35, |v26|, v83
	v_mul_f32_e64 v36, |v34|, v83
	v_mul_f32_e64 v37, |v5|, v83
	v_cmp_gt_f32_e64 s[8:9], s53, v28
	v_cmp_gt_f32_e64 s[20:21], s53, v35
	v_cmp_gt_f32_e64 s[22:23], s53, v36
	v_cmp_gt_f32_e64 s[24:25], s53, v37
	v_cndmask_b32_e64 v28, 0, v78, s[8:9]
	v_cndmask_b32_e64 v35, 0, v78, s[20:21]
	v_cndmask_b32_e64 v36, 0, v78, s[22:23]
	v_cndmask_b32_e64 v38, 0, v78, s[24:25]
	v_fma_f32 v11, |v11|, v83, v28
	v_fma_f32 v91, |v26|, v83, v35
	ds_read_b128 v[26:29], v19 offset:21824
	ds_read_b128 v[30:33], v19 offset:30464
	v_fma_f32 v93, |v34|, v83, v36
	ds_read_b128 v[34:37], v19 offset:26176
	v_fma_f32 v5, |v5|, v83, v38
	ds_read_b128 v[38:41], v19 offset:30528
	s_waitcnt lgkmcnt(5)
	v_mfma_f32_16x16x32_bf16 v[0:3], v[14:17], v[60:63], v[0:3]
	ds_read_b128 v[14:17], v19 offset:17536
	v_exp_f32_e32 v102, v48
	v_exp_f32_e32 v103, v49
	v_mfma_f32_16x16x32_bf16 v[6:9], v[6:9], v[56:59], 0
	v_exp_f32_e32 v104, v50
	v_exp_f32_e32 v96, v42
	v_exp_f32_e32 v97, v10
	s_waitcnt lgkmcnt(5)
	v_mfma_f32_16x16x32_bf16 v[22:25], v[22:25], v[56:59], 0
	v_exp_f32_e32 v98, v43
	v_exp_f32_e32 v99, v44
	v_exp_f32_e32 v101, v45
	s_waitcnt lgkmcnt(3)
	v_mfma_f32_16x16x32_bf16 v[30:33], v[30:33], v[56:59], 0
	v_mul_f32_e64 v75, |v64|, v83
	v_cndmask_b32_e32 v46, 0, v79, vcc
	v_cndmask_b32_e64 v47, 0, v79, s[0:1]
	v_mfma_f32_16x16x32_bf16 v[6:9], v[26:29], v[60:63], v[6:9]
	ds_read_b128 v[52:55], v18 offset:128
	ds_read_b128 v[26:29], v19 offset:21888
	v_exp_f32_e32 v100, v11
	v_ldexp_f32 v10, v96, v46
	s_waitcnt lgkmcnt(4)
	v_mfma_f32_16x16x32_bf16 v[22:25], v[34:37], v[60:63], v[22:25]
	v_ldexp_f32 v11, v97, v47
	v_cmp_gt_f32_e32 vcc, s53, v75
	v_cndmask_b32_e64 v77, 0, v79, s[4:5]
	s_waitcnt lgkmcnt(3)
	v_mfma_f32_16x16x32_bf16 v[30:33], v[38:41], v[60:63], v[30:33]
	ds_read_b128 v[48:51], v18 offset:192
	ds_read_b128 v[34:37], v19 offset:17600
	ds_read_b128 v[38:41], v19 offset:26240
	v_cndmask_b32_e64 v84, 0, v79, s[6:7]
	v_ldexp_f32 v18, v98, v77
	s_waitcnt lgkmcnt(4)
	v_mfma_f32_16x16x32_bf16 v[0:3], v[14:17], v[52:55], v[0:3]
	ds_read_b128 v[14:17], v19 offset:21952
	ds_read_b128 v[42:45], v19 offset:30592
	v_exp_f32_e32 v13, v13
	v_exp_f32_e32 v91, v91
	s_waitcnt lgkmcnt(3)
	v_mfma_f32_16x16x32_bf16 v[0:3], v[34:37], v[48:51], v[0:3]
	v_exp_f32_e32 v93, v93
	v_cndmask_b32_e64 v90, 0, v79, s[18:19]
	v_cndmask_b32_e64 v89, 0, v79, s[16:17]
	v_mfma_f32_16x16x32_bf16 v[6:9], v[26:29], v[52:55], v[6:9]
	ds_read_b128 v[26:29], v19 offset:26304
	s_nop 2
	v_pk_mul_f32 v[10:11], v[10:11], v[0:1]
	v_cndmask_b32_e32 v0, 0, v78, vcc
	v_fma_f32 v0, |v64|, v83, v0
	v_subrev_u32_e32 v1, 50, v69
	s_waitcnt lgkmcnt(3)
	v_mfma_f32_16x16x32_bf16 v[22:25], v[38:41], v[52:55], v[22:25]
	v_exp_f32_e32 v0, v0
	v_cvt_f32_i32_e32 v1, v1
	ds_read_b128 v[38:41], v19 offset:30656
	v_ldexp_f32 v19, v99, v84
	v_pk_mul_f32 v[18:19], v[18:19], v[2:3]
	v_cndmask_b32_e32 v2, 0, v79, vcc
	s_waitcnt lgkmcnt(3)
	v_mfma_f32_16x16x32_bf16 v[6:9], v[14:17], v[48:51], v[6:9]
	v_lshlrev_b32_e32 v64, 3, v21
	v_cndmask_b32_e64 v92, 0, v79, s[20:21]
	v_cndmask_b32_e64 v94, 0, v79, s[22:23]
	s_waitcnt lgkmcnt(1)
	v_mfma_f32_16x16x32_bf16 v[14:17], v[26:29], v[48:51], v[22:25]
	v_ldexp_f32 v29, v0, v2
	v_mul_f32_e64 v0, |v1|, v83
	v_cmp_gt_f32_e32 vcc, s53, v0
	v_mfma_f32_16x16x32_bf16 v[30:33], v[42:45], v[52:55], v[30:33]
	v_ldexp_f32 v43, v13, v90
	v_cndmask_b32_e32 v0, 0, v78, vcc
	v_fma_f32 v13, |v1|, v83, v0
	v_mul_u32_u24_e32 v0, 0x90, v20
	v_add3_u32 v21, v4, v64, v0
	v_exp_f32_e32 v5, v5
	v_ldexp_f32 v42, v104, v89
	v_ldexp_f32 v26, v91, v92
	v_ldexp_f32 v27, v93, v94
	v_add_u32_e32 v92, 0x9800, v21
	v_pk_mul_f32 v[46:47], v[42:43], v[14:15]
	v_pk_mul_f32 v[90:91], v[26:27], v[16:17]
	ds_read2_b64 v[14:17], v92 offset0:64 offset1:68
	v_exp_f32_e32 v13, v13
	v_cndmask_b32_e64 v95, 0, v79, s[24:25]
	v_ldexp_f32 v28, v5, v95
	v_cvt_pk_bf16_f32 v5, v18, v19
	v_cndmask_b32_e32 v18, 0, v79, vcc
	v_ldexp_f32 v18, v13, v18
	v_subrev_u32_e32 v13, 51, v69
	v_cndmask_b32_e64 v85, 0, v79, s[8:9]
	v_cndmask_b32_e64 v86, 0, v79, s[10:11]
	v_cndmask_b32_e64 v87, 0, v79, s[12:13]
	v_cndmask_b32_e64 v88, 0, v79, s[14:15]
	s_waitcnt lgkmcnt(1)
	v_mfma_f32_16x16x32_bf16 v[22:25], v[38:41], v[48:51], v[30:33]
	v_cvt_f32_i32_e32 v13, v13
	v_ldexp_f32 v34, v100, v85
	v_ldexp_f32 v35, v101, v86
	v_ldexp_f32 v36, v102, v87
	v_ldexp_f32 v37, v103, v88
	v_pk_mul_f32 v[6:7], v[34:35], v[6:7]
	v_pk_mul_f32 v[30:31], v[36:37], v[8:9]
	v_add_u32_e32 v75, 0x8800, v21
	v_cvt_pk_bf16_f32 v4, v10, v11
	v_add_u32_e32 v77, 0x9000, v21
	v_cvt_pk_bf16_f32 v6, v6, v7
	v_cvt_pk_bf16_f32 v7, v30, v31
	v_add_u32_e32 v93, 0xa000, v21
	v_add_u32_e32 v94, 0xa800, v21
	v_add_u32_e32 v69, 0xb000, v21
	v_add_u32_e32 v95, 0xb800, v21
	v_add_u32_e32 v96, 0xc000, v21
	v_pk_mul_f32 v[22:23], v[28:29], v[22:23]
	ds_read2_b64 v[0:3], v75 offset1:4
	ds_read2_b64 v[8:11], v77 offset0:32 offset1:36
	ds_read2_b64 v[26:29], v93 offset0:96 offset1:100
	ds_read2_b64 v[30:33], v94 offset0:128 offset1:132
	s_waitcnt lgkmcnt(4)
	v_mfma_f32_16x16x32_bf16 v[34:37], v[14:17], v[4:7], 0
	ds_read2_b64 v[14:17], v69 offset0:160 offset1:164
	v_mul_f32_e64 v19, |v13|, v83
	ds_read2_b64 v[38:41], v95 offset0:192 offset1:196
	ds_read2_b64 v[42:45], v96 offset0:224 offset1:228
	v_cmp_gt_f32_e32 vcc, s53, v19
	s_waitcnt lgkmcnt(6)
	v_mfma_f32_16x16x32_bf16 v[0:3], v[0:3], v[4:7], 0
	v_cvt_pk_bf16_f32 v89, v90, v91
	v_cndmask_b32_e32 v19, 0, v78, vcc
	v_fma_f32 v13, |v13|, v83, v19
	v_exp_f32_e32 v13, v13
	v_cndmask_b32_e32 v19, 0, v79, vcc
	s_waitcnt lgkmcnt(5)
	v_mfma_f32_16x16x32_bf16 v[8:11], v[8:11], v[4:7], 0
	v_cvt_pk_bf16_f32 v90, v22, v23
	v_ldexp_f32 v19, v13, v19
	v_pk_mul_f32 v[18:19], v[18:19], v[24:25]
	s_waitcnt lgkmcnt(4)
	v_mfma_f32_16x16x32_bf16 v[26:29], v[26:29], v[4:7], 0
	ds_read2_b64 v[22:25], v92 offset0:72 offset1:76
	v_cvt_pk_bf16_f32 v88, v46, v47
	v_cvt_pk_bf16_f32 v91, v18, v19
	s_waitcnt lgkmcnt(4)
	v_mfma_f32_16x16x32_bf16 v[30:33], v[30:33], v[4:7], 0
	v_ashrrev_i32_e32 v13, 31, v12
	v_lshlrev_b64 v[12:13], 15, v[12:13]
	v_lshlrev_b32_e32 v20, 8, v20
	s_waitcnt lgkmcnt(3)
	v_mfma_f32_16x16x32_bf16 v[84:87], v[14:17], v[4:7], 0
	ds_read2_b64 v[14:17], v75 offset0:8 offset1:12
	v_mov_b32_e32 v75, v65
	v_mov_b32_e32 v21, v65
	s_waitcnt lgkmcnt(3)
	v_mfma_f32_16x16x32_bf16 v[38:41], v[38:41], v[4:7], 0
	v_readlane_b32 s4, v255, 2
	v_readlane_b32 s6, v255, 4
	v_readlane_b32 s7, v255, 5
	s_waitcnt lgkmcnt(2)
	v_mfma_f32_16x16x32_bf16 v[42:45], v[42:45], v[4:7], 0
	ds_read2_b64 v[4:7], v77 offset0:40 offset1:44
	v_mov_b32_e32 v77, v65
	v_readlane_b32 s5, v255, 3
	s_waitcnt lgkmcnt(1)
	v_mfma_f32_16x16x32_bf16 v[16:19], v[14:17], v[88:91], v[0:3]
	v_readlane_b32 s8, v255, 6
	v_readlane_b32 s9, v255, 7
	v_readlane_b32 s10, v255, 8
	s_waitcnt lgkmcnt(0)
	v_mfma_f32_16x16x32_bf16 v[0:3], v[4:7], v[88:91], v[8:11]
	v_readlane_b32 s11, v255, 9
	s_nop 1
	ds_read2_b64 v[8:11], v93 offset0:104 offset1:108
	v_readlane_b32 s12, v255, 10
	v_mfma_f32_16x16x32_bf16 v[4:7], v[22:25], v[88:91], v[34:37]
	ds_read2_b64 v[22:25], v94 offset0:136 offset1:140
	v_readlane_b32 s13, v255, 11
	v_readlane_b32 s14, v255, 12
	s_waitcnt lgkmcnt(1)
	v_mfma_f32_16x16x32_bf16 v[8:11], v[8:11], v[88:91], v[26:29]
	s_nop 2
	v_lshl_add_u64 v[26:27], s[42:43], 0, v[12:13]
	v_lshl_add_u64 v[26:27], v[26:27], 0, v[74:75]
	v_lshl_add_u64 v[108:109], v[26:27], 0, v[20:21]
	s_waitcnt lgkmcnt(0)
	v_mfma_f32_16x16x32_bf16 v[12:15], v[22:25], v[88:91], v[30:33]
	ds_read2_b64 v[22:25], v69 offset0:168 offset1:172
	v_add_co_u32_e32 v134, vcc, s63, v108
	s_nop 1
	v_addc_co_u32_e32 v135, vcc, 0, v109, vcc
	v_add_co_u32_e32 v136, vcc, s64, v108
	s_nop 1
	v_addc_co_u32_e32 v137, vcc, 0, v109, vcc
	v_add_co_u32_e32 v138, vcc, s65, v108
	s_nop 1
	v_addc_co_u32_e32 v139, vcc, 0, v109, vcc
	v_add_co_u32_e32 v140, vcc, s66, v108
	s_nop 1
	v_addc_co_u32_e32 v141, vcc, 0, v109, vcc
	v_add_co_u32_e32 v142, vcc, s67, v108
	s_nop 1
	v_addc_co_u32_e32 v143, vcc, 0, v109, vcc
	v_add_co_u32_e32 v150, vcc, s68, v108
	s_nop 1
	v_addc_co_u32_e32 v151, vcc, 0, v109, vcc
	v_add_co_u32_e32 v152, vcc, s69, v108
	s_nop 1
	v_addc_co_u32_e32 v153, vcc, 0, v109, vcc
	global_load_dwordx4 v[160:163], v[108:109], off
	global_load_dwordx4 v[164:167], v[108:109], off offset:64
	global_load_dwordx4 v[168:171], v[108:109], off offset:128
	global_load_dwordx4 v[172:175], v[108:109], off offset:192
	global_load_dwordx4 v[176:179], v[134:135], off
	global_load_dwordx4 v[180:183], v[134:135], off offset:64
	global_load_dwordx4 v[184:187], v[134:135], off offset:128
	global_load_dwordx4 v[188:191], v[134:135], off offset:192
	global_load_dwordx4 v[192:195], v[136:137], off
	global_load_dwordx4 v[196:199], v[136:137], off offset:64
	global_load_dwordx4 v[200:203], v[136:137], off offset:128
	global_load_dwordx4 v[204:207], v[136:137], off offset:192
	global_load_dwordx4 v[208:211], v[138:139], off
	global_load_dwordx4 v[212:215], v[138:139], off offset:64
	global_load_dwordx4 v[216:219], v[138:139], off offset:128
	global_load_dwordx4 v[220:223], v[138:139], off offset:192
	global_load_dwordx4 v[224:227], v[140:141], off
	global_load_dwordx4 v[228:231], v[140:141], off offset:64
	global_load_dwordx4 v[232:235], v[140:141], off offset:128
	global_load_dwordx4 v[236:239], v[140:141], off offset:192
	global_load_dwordx4 v[240:243], v[142:143], off
	global_load_dwordx4 v[244:247], v[142:143], off offset:64
	global_load_dwordx4 v[248:251], v[142:143], off offset:128
	ds_read2_b64 v[30:33], v95 offset0:200 offset1:204
	s_waitcnt lgkmcnt(0)
	v_mfma_f32_16x16x32_bf16 v[20:23], v[22:25], v[88:91], v[84:87]
	v_ashrrev_i32_e32 v69, 31, v68
	v_mfma_f32_16x16x32_bf16 v[84:87], v[30:33], v[88:91], v[38:41]
	ds_read2_b64 v[30:33], v96 offset0:232 offset1:236
	s_waitcnt lgkmcnt(0)
	v_mfma_f32_16x16x32_bf16 v[88:91], v[30:33], v[88:91], v[42:45]
	s_nop 0
	s_waitcnt lgkmcnt(0)
	global_load_dwordx4 v[96:99], v[142:143], off offset:192
	global_load_dwordx4 v[100:103], v[150:151], off
	global_load_dwordx4 v[104:107], v[150:151], off offset:64
	s_waitcnt vmcnt(22)
	v_mfma_f32_16x16x32_bf16 v[36:39], v[160:163], v[56:59], 0
	v_mfma_f32_16x16x32_bf16 v[36:39], v[164:167], v[60:63], v[36:39]
	v_mfma_f32_16x16x32_bf16 v[36:39], v[168:171], v[52:55], v[36:39]
	v_mfma_f32_16x16x32_bf16 v[36:39], v[172:175], v[48:51], v[36:39]
	global_load_dwordx4 v[160:163], v[150:151], off offset:128
	global_load_dwordx4 v[164:167], v[150:151], off offset:192
	global_load_dwordx4 v[168:171], v[152:153], off
	global_load_dwordx4 v[172:175], v[152:153], off offset:64
	s_waitcnt vmcnt(22)
	v_mfma_f32_16x16x32_bf16 v[24:27], v[176:179], v[56:59], 0
	v_mfma_f32_16x16x32_bf16 v[24:27], v[180:183], v[60:63], v[24:27]
	v_mfma_f32_16x16x32_bf16 v[24:27], v[184:187], v[52:55], v[24:27]
	v_mfma_f32_16x16x32_bf16 v[24:27], v[188:191], v[48:51], v[24:27]
	global_load_dwordx4 v[176:179], v[152:153], off offset:128
	global_load_dwordx4 v[180:183], v[152:153], off offset:192
	s_waitcnt vmcnt(20)
	v_mfma_f32_16x16x32_bf16 v[28:31], v[192:195], v[56:59], 0
	v_mfma_f32_16x16x32_bf16 v[28:31], v[196:199], v[60:63], v[28:31]
	v_mfma_f32_16x16x32_bf16 v[28:31], v[200:203], v[52:55], v[28:31]
	v_mfma_f32_16x16x32_bf16 v[28:31], v[204:207], v[48:51], v[28:31]
	s_waitcnt vmcnt(16)
	v_mfma_f32_16x16x32_bf16 v[32:35], v[208:211], v[56:59], 0
	v_mfma_f32_16x16x32_bf16 v[32:35], v[212:215], v[60:63], v[32:35]
	v_mfma_f32_16x16x32_bf16 v[32:35], v[216:219], v[52:55], v[32:35]
	v_mfma_f32_16x16x32_bf16 v[32:35], v[220:223], v[48:51], v[32:35]
	s_waitcnt vmcnt(12)
	v_mfma_f32_16x16x32_bf16 v[40:43], v[224:227], v[56:59], 0
	v_mfma_f32_16x16x32_bf16 v[40:43], v[228:231], v[60:63], v[40:43]
	v_mfma_f32_16x16x32_bf16 v[40:43], v[232:235], v[52:55], v[40:43]
	v_mfma_f32_16x16x32_bf16 v[40:43], v[236:239], v[48:51], v[40:43]
	s_waitcnt vmcnt(8)
	v_mfma_f32_16x16x32_bf16 v[44:47], v[240:243], v[56:59], 0
	v_mfma_f32_16x16x32_bf16 v[44:47], v[244:247], v[60:63], v[44:47]
	v_mfma_f32_16x16x32_bf16 v[44:47], v[248:251], v[52:55], v[44:47]
	v_mfma_f32_16x16x32_bf16 v[44:47], v[96:99], v[48:51], v[44:47]
	s_waitcnt vmcnt(4)
	v_mfma_f32_16x16x32_bf16 v[92:95], v[100:103], v[56:59], 0
	v_mfma_f32_16x16x32_bf16 v[92:95], v[104:107], v[60:63], v[92:95]
	v_mfma_f32_16x16x32_bf16 v[92:95], v[160:163], v[52:55], v[92:95]
	v_mfma_f32_16x16x32_bf16 v[92:95], v[164:167], v[48:51], v[92:95]
	s_waitcnt vmcnt(0)
	v_mfma_f32_16x16x32_bf16 v[56:59], v[168:171], v[56:59], 0
	v_mfma_f32_16x16x32_bf16 v[56:59], v[172:175], v[60:63], v[56:59]
	v_mfma_f32_16x16x32_bf16 v[52:55], v[176:179], v[52:55], v[56:59]
	v_mfma_f32_16x16x32_bf16 v[48:51], v[180:183], v[48:51], v[52:55]
	v_readlane_b32 s15, v255, 13
	v_readlane_b32 s16, v255, 14
	v_readlane_b32 s17, v255, 15
	v_readlane_b32 s18, v255, 16
	v_readlane_b32 s19, v255, 17
	s_waitcnt lgkmcnt(0)
	s_nop 5
	s_waitcnt lgkmcnt(0)
	s_nop 2
	s_nop 2
	s_waitcnt lgkmcnt(0)
	s_nop 0
	s_nop 3
	s_waitcnt lgkmcnt(0)
	s_waitcnt lgkmcnt(0)
	s_waitcnt lgkmcnt(0)
	s_nop 0
	s_waitcnt lgkmcnt(0)
	s_nop 0
	s_waitcnt lgkmcnt(0)
	s_waitcnt lgkmcnt(0)
	s_nop 0
	s_waitcnt lgkmcnt(0)
	v_lshl_add_u64 v[100:101], v[68:69], 0, v[76:77]
	v_mad_u64_u32 v[60:61], s[0:1], v100, s57, v[66:67]
	v_mad_i32_i24 v61, v101, s57, v61
	v_lshl_add_u64 v[60:61], v[60:61], 0, v[72:73]
	v_lshl_add_u64 v[102:103], v[60:61], 0, v[64:65]
	v_add_co_u32_e32 v60, vcc, s63, v102
	s_waitcnt lgkmcnt(0)
	v_addc_co_u32_e32 v61, vcc, 0, v103, vcc
	v_mov_b64_e32 v[68:69], v[252:253]
	v_lshl_add_u64 v[232:233], v[102:103], 0, s[46:47]
	v_lshl_add_u64 v[234:235], v[70:71], 2, s[6:7]
	v_lshl_add_u64 v[234:235], v[234:235], 0, v[74:75]
	global_load_dwordx2 v[186:187], v[232:233], off offset:32
	global_load_dwordx2 v[188:189], v[232:233], off offset:64
	global_load_dwordx2 v[190:191], v[232:233], off offset:96
	global_load_dwordx2 v[192:193], v[232:233], off offset:128
	global_load_dwordx2 v[194:195], v[232:233], off offset:160
	global_load_dwordx2 v[196:197], v[232:233], off offset:192
	global_load_dwordx2 v[198:199], v[232:233], off offset:224
	global_load_dwordx4 v[204:207], v[234:235], off offset:64
	global_load_dwordx4 v[208:211], v[234:235], off offset:128
	global_load_dwordx4 v[212:215], v[234:235], off offset:192
	global_load_dwordx4 v[216:219], v[234:235], off offset:256
	global_load_dwordx4 v[220:223], v[234:235], off offset:320
	global_load_dwordx4 v[224:227], v[234:235], off offset:384
	global_load_dwordx4 v[228:231], v[234:235], off offset:448
	s_nop 0
	v_add_u32_e32 v56, 1, v76
	v_cvt_f32_ubyte0_e32 v56, v56
	v_mul_f32_e32 v57, v83, v56
	v_cmp_gt_f32_e32 vcc, s53, v57
	s_waitcnt lgkmcnt(0)
	v_lshlrev_b32_e32 v77, 16, v68
	v_cndmask_b32_e32 v57, 0, v78, vcc
	v_fmac_f32_e32 v57, v83, v56
	v_exp_f32_e32 v56, v57
	v_cndmask_b32_e32 v52, 0, v79, vcc
	v_and_b32_e32 v68, 0xffff0000, v68
	v_cmp_lt_i32_e32 vcc, v157, v156
	v_ldexp_f32 v62, v56, v52
	v_pk_fma_f32 v[58:59], v[62:63], v[50:51], v[90:91] op_sel_hi:[0,1,1]
	v_lshlrev_b64 v[50:51], 11, v[100:101]
	v_lshl_add_u64 v[50:51], s[30:31], 0, v[50:51]
	v_lshl_add_u64 v[52:53], v[50:51], 0, v[72:73]
	v_mul_f32_e32 v72, 0xbfb8aa3b, v77
	v_pk_fma_f32 v[54:55], v[62:63], v[92:93], v[84:85] op_sel_hi:[0,1,1]
	v_exp_f32_e32 v84, v72
	v_mul_f32_e32 v72, 0xbfb8aa3b, v68
	v_exp_f32_e32 v85, v72
	v_pk_fma_f32 v[60:61], v[62:63], v[48:49], v[88:89] op_sel_hi:[0,1,1]
	v_cndmask_b32_e32 v48, v155, v157, vcc
	v_cmp_lt_i32_e32 vcc, v158, v156
	v_lshlrev_b32_e32 v76, 2, v48
	v_pk_fma_f32 v[56:57], v[62:63], v[94:95], v[86:87] op_sel_hi:[0,1,1]
	v_cndmask_b32_e32 v48, v155, v158, vcc
	v_lshlrev_b32_e32 v63, 2, v48
	v_pk_fma_f32 v[18:19], v[62:63], v[38:39], v[18:19] op_sel_hi:[0,1,1]
	v_pk_add_f32 v[38:39], v[84:85], 1.0 op_sel_hi:[1,0]
	v_lshlrev_b32_e32 v83, 16, v69
	v_and_b32_e32 v86, 0xffff0000, v69
	v_div_scale_f32 v69, s[0:1], v39, v39, v68
	v_rcp_f32_e32 v84, v69
	v_pk_fma_f32 v[16:17], v[62:63], v[36:37], v[16:17] op_sel_hi:[0,1,1]
	v_add_f32_e32 v36, 0, v16
	v_add_f32_e32 v85, v17, v36
	v_fma_f32 v36, -v69, v84, 1.0
	v_fmac_f32_e32 v84, v36, v84
	v_div_scale_f32 v36, vcc, v68, v39, v68
	v_mul_f32_e32 v37, v36, v84
	v_fma_f32 v87, -v69, v37, v36
	v_fmac_f32_e32 v37, v87, v84
	v_div_scale_f32 v87, s[0:1], v38, v38, v77
	v_rcp_f32_e32 v88, v87
	v_fma_f32 v36, -v69, v37, v36
	v_div_fmas_f32 v36, v36, v84, v37
	v_div_fixup_f32 v37, v36, v39, v68
	v_fma_f32 v36, -v87, v88, 1.0
	v_fmac_f32_e32 v88, v36, v88
	v_div_scale_f32 v36, vcc, v77, v38, v77
	v_mul_f32_e32 v39, v36, v88
	v_fma_f32 v68, -v87, v39, v36
	v_fmac_f32_e32 v39, v68, v88
	v_fma_f32 v36, -v87, v39, v36
	v_div_fmas_f32 v36, v36, v88, v39
	v_div_fixup_f32 v36, v36, v38, v77
	v_add_f32_e32 v38, v18, v85
	v_add_f32_e32 v38, v19, v38
	v_pk_fma_f32 v[0:1], v[62:63], v[24:25], v[0:1] op_sel_hi:[0,1,1]
	v_add_f32_e32 v24, v38, v0
	v_pk_fma_f32 v[2:3], v[62:63], v[26:27], v[2:3] op_sel_hi:[0,1,1]
	v_add_f32_e32 v24, v1, v24
	v_add_f32_e32 v24, v2, v24
	v_add_f32_e32 v24, v3, v24
	v_pk_fma_f32 v[4:5], v[62:63], v[28:29], v[4:5] op_sel_hi:[0,1,1]
	v_add_f32_e32 v24, v24, v4
	v_pk_fma_f32 v[6:7], v[62:63], v[30:31], v[6:7] op_sel_hi:[0,1,1]
	v_add_f32_e32 v24, v5, v24
	v_add_f32_e32 v24, v6, v24
	v_add_f32_e32 v24, v7, v24
	v_pk_fma_f32 v[8:9], v[62:63], v[32:33], v[8:9] op_sel_hi:[0,1,1]
	v_add_f32_e32 v24, v24, v8
	v_pk_fma_f32 v[10:11], v[62:63], v[34:35], v[10:11] op_sel_hi:[0,1,1]
	v_add_f32_e32 v24, v9, v24
	v_add_f32_e32 v24, v10, v24
	v_add_f32_e32 v24, v11, v24
	v_pk_fma_f32 v[12:13], v[62:63], v[40:41], v[12:13] op_sel_hi:[0,1,1]
	v_add_f32_e32 v24, v24, v12
	v_pk_fma_f32 v[14:15], v[62:63], v[42:43], v[14:15] op_sel_hi:[0,1,1]
	v_add_f32_e32 v24, v13, v24
	v_lshl_add_u64 v[48:49], v[70:71], 2, s[6:7]
	v_add_f32_e32 v24, v14, v24
	v_lshl_add_u64 v[48:49], v[48:49], 0, v[74:75]
	v_add_f32_e32 v28, v15, v24
	v_pk_fma_f32 v[26:27], v[62:63], v[44:45], v[20:21] op_sel_hi:[0,1,1]
	global_load_dwordx4 v[72:75], v[48:49], off
	v_add_f32_e32 v20, v28, v26
	v_pk_fma_f32 v[24:25], v[62:63], v[46:47], v[22:23] op_sel_hi:[0,1,1]
	v_add_f32_e32 v20, v27, v20
	v_add_f32_e32 v20, v24, v20
	v_add_f32_e32 v20, v25, v20
	v_add_f32_e32 v20, v20, v54
	v_add_f32_e32 v20, v55, v20
	v_mul_f32_e32 v68, 0xbfb8aa3b, v83
	v_mul_f32_e32 v69, 0xbfb8aa3b, v86
	v_add_f32_e32 v20, v56, v20
	v_exp_f32_e32 v68, v68
	v_exp_f32_e32 v69, v69
	v_add_f32_e32 v20, v57, v20
	v_add_f32_e32 v20, v20, v60
	v_add_f32_e32 v20, v61, v20
	v_add_f32_e32 v20, v58, v20
	v_pk_add_f32 v[68:69], v[68:69], 1.0 op_sel_hi:[1,0]
	v_add_f32_e32 v20, v59, v20
	v_div_scale_f32 v39, s[0:1], v69, v69, v86
	ds_bpermute_b32 v21, v76, v20
	v_rcp_f32_e32 v84, v39
	v_lshl_add_u64 v[50:51], v[102:103], 0, s[46:47]
	v_fma_f32 v77, -v39, v84, 1.0
	s_waitcnt lgkmcnt(0)
	v_add_f32_e32 v20, v20, v21
	v_fmac_f32_e32 v84, v77, v84
	v_div_scale_f32 v77, vcc, v86, v69, v86
	ds_bpermute_b32 v21, v63, v20
	v_mul_f32_e32 v85, v77, v84
	v_fma_f32 v87, -v39, v85, v77
	v_fmac_f32_e32 v85, v87, v84
	v_fma_f32 v22, -v39, v85, v77
	v_div_fmas_f32 v22, v22, v84, v85
	s_waitcnt lgkmcnt(0)
	v_add_f32_e32 v20, v20, v21
	v_div_fixup_f32 v29, v22, v69, v86
	v_mul_f32_e32 v28, 0x3c000000, v20
	v_pk_add_f32 v[32:33], v[16:17], v[28:29] op_sel_hi:[1,0] neg_lo:[0,1] neg_hi:[0,1]
	v_pk_add_f32 v[38:39], v[18:19], v[28:29] op_sel_hi:[1,0] neg_lo:[0,1] neg_hi:[0,1]
	v_pk_mul_f32 v[34:35], v[32:33], v[32:33]
	v_pk_mul_f32 v[40:41], v[38:39], v[38:39]
	v_pk_add_f32 v[42:43], v[0:1], v[28:29] op_sel_hi:[1,0] neg_lo:[0,1] neg_hi:[0,1]
	v_pk_add_f32 v[46:47], v[2:3], v[28:29] op_sel_hi:[1,0] neg_lo:[0,1] neg_hi:[0,1]
	v_pk_add_f32 v[84:85], v[4:5], v[28:29] op_sel_hi:[1,0] neg_lo:[0,1] neg_hi:[0,1]
	v_pk_add_f32 v[88:89], v[6:7], v[28:29] op_sel_hi:[1,0] neg_lo:[0,1] neg_hi:[0,1]
	v_pk_add_f32 v[22:23], v[8:9], v[28:29] op_sel_hi:[1,0] neg_lo:[0,1] neg_hi:[0,1]
	v_pk_add_f32 v[20:21], v[10:11], v[28:29] op_sel_hi:[1,0] neg_lo:[0,1] neg_hi:[0,1]
	v_pk_add_f32 v[18:19], v[12:13], v[28:29] op_sel_hi:[1,0] neg_lo:[0,1] neg_hi:[0,1]
	v_pk_add_f32 v[16:17], v[14:15], v[28:29] op_sel_hi:[1,0] neg_lo:[0,1] neg_hi:[0,1]
	v_pk_add_f32 v[14:15], v[26:27], v[28:29] op_sel_hi:[1,0] neg_lo:[0,1] neg_hi:[0,1]
	v_pk_add_f32 v[12:13], v[24:25], v[28:29] op_sel_hi:[1,0] neg_lo:[0,1] neg_hi:[0,1]
	v_pk_add_f32 v[4:5], v[60:61], v[28:29] op_sel_hi:[1,0] neg_lo:[0,1] neg_hi:[0,1]
	v_pk_add_f32 v[0:1], v[58:59], v[28:29] op_sel_hi:[1,0] neg_lo:[0,1] neg_hi:[0,1]
	v_pk_add_f32 v[8:9], v[56:57], v[28:29] op_sel_hi:[1,0] neg_lo:[0,1] neg_hi:[0,1]
	v_pk_add_f32 v[10:11], v[54:55], v[28:29] op_sel_hi:[1,0] neg_lo:[0,1] neg_hi:[0,1]
	v_add_f32_e32 v28, v34, v35
	v_add_f32_e32 v28, v40, v28
	v_pk_mul_f32 v[44:45], v[42:43], v[42:43]
	v_add_f32_e32 v28, v41, v28
	v_add_f32_e32 v28, v44, v28
	v_pk_mul_f32 v[2:3], v[46:47], v[46:47]
	v_add_f32_e32 v28, v45, v28
	v_add_f32_e32 v2, v2, v28
	v_pk_mul_f32 v[86:87], v[84:85], v[84:85]
	v_add_f32_e32 v2, v3, v2
	v_add_f32_e32 v2, v86, v2
	v_pk_mul_f32 v[6:7], v[88:89], v[88:89]
	v_add_f32_e32 v2, v87, v2
	v_add_f32_e32 v2, v6, v2
	v_pk_mul_f32 v[90:91], v[22:23], v[22:23]
	v_add_f32_e32 v2, v7, v2
	v_add_f32_e32 v2, v90, v2
	v_pk_mul_f32 v[92:93], v[20:21], v[20:21]
	v_add_f32_e32 v2, v91, v2
	v_add_f32_e32 v2, v92, v2
	v_pk_mul_f32 v[94:95], v[18:19], v[18:19]
	v_add_f32_e32 v2, v93, v2
	v_add_f32_e32 v2, v94, v2
	v_pk_mul_f32 v[96:97], v[16:17], v[16:17]
	v_add_f32_e32 v2, v95, v2
	v_add_f32_e32 v2, v96, v2
	v_pk_mul_f32 v[26:27], v[14:15], v[14:15]
	v_add_f32_e32 v2, v97, v2
	v_add_f32_e32 v2, v26, v2
	v_pk_mul_f32 v[24:25], v[12:13], v[12:13]
	v_add_f32_e32 v2, v27, v2
	v_add_f32_e32 v2, v24, v2
	v_pk_mul_f32 v[54:55], v[10:11], v[10:11]
	v_add_f32_e32 v2, v25, v2
	v_add_f32_e32 v2, v54, v2
	v_pk_mul_f32 v[56:57], v[8:9], v[8:9]
	v_add_f32_e32 v2, v55, v2
	v_add_f32_e32 v2, v56, v2
	v_pk_mul_f32 v[60:61], v[4:5], v[4:5]
	v_add_f32_e32 v2, v57, v2
	v_add_f32_e32 v2, v60, v2
	v_pk_mul_f32 v[58:59], v[0:1], v[0:1]
	v_add_f32_e32 v2, v61, v2
	v_add_f32_e32 v2, v58, v2
	v_add_f32_e32 v2, v59, v2
	ds_bpermute_b32 v3, v76, v2
	v_div_scale_f32 v62, s[0:1], v68, v68, v83
	v_rcp_f32_e32 v69, v62
	s_waitcnt vmcnt(0)
	v_lshlrev_b32_e32 v40, 16, v31
	s_waitcnt lgkmcnt(0)
	v_add_f32_e32 v2, v2, v3
	ds_bpermute_b32 v3, v63, v2
	v_fma_f32 v6, -v62, v69, 1.0
	v_fmac_f32_e32 v69, v6, v69
	v_div_scale_f32 v6, vcc, v83, v68, v83
	s_waitcnt lgkmcnt(0)
	v_add_f32_e32 v2, v2, v3
	v_fmamk_f32 v2, v2, 0x3c000000, v81
	v_mul_f32_e32 v7, v6, v69
	v_mul_f32_e32 v3, 0x4b800000, v2
	v_cmp_gt_f32_e64 s[0:1], s54, v2
	v_fma_f32 v24, -v62, v7, v6
	v_fmac_f32_e32 v7, v24, v69
	v_cndmask_b32_e64 v2, v2, v3, s[0:1]
	v_rsq_f32_e32 v24, v2
	v_fma_f32 v6, -v62, v7, v6
	v_div_fmas_f32 v2, v6, v69, v7
	v_div_fixup_f32 v28, v2, v68, v83
	v_mul_f32_e32 v6, 0x45800000, v24
	v_cndmask_b32_e64 v6, v24, v6, s[0:1]
	v_pk_mul_f32 v[24:25], v[32:33], v[6:7] op_sel_hi:[1,0]
	v_pk_mul_f32 v[26:27], v[38:39], v[6:7] op_sel_hi:[1,0]
	v_pk_mul_f32 v[24:25], v[72:73], v[24:25]
	v_pk_mul_f32 v[26:27], v[74:75], v[26:27]
	v_pk_mul_f32 v[24:25], v[36:37], v[24:25]
	v_pk_mul_f32 v[26:27], v[28:29], v[26:27]
	v_lshl_add_u64 v[2:3], v[52:53], 0, v[64:65]
	v_bfe_u32 v180, v154, 4, 2
	v_lshlrev_b32_e32 v180, 3, v180
	v_mov_b32_e32 v181, 0
	v_lshl_add_u64 v[180:181], v[2:3], 0, v[180:181]
	v_cvt_pk_bf16_f32 v24, v24, v25
	v_cvt_pk_bf16_f32 v25, v26, v27
	v_lshlrev_b32_e32 v32, 16, v186
	v_and_b32_e32 v33, 0xffff0000, v186
	v_lshlrev_b32_e32 v34, 16, v187
	v_and_b32_e32 v35, 0xffff0000, v187
	v_mul_f32_e32 v36, 0xbfb8aa3b, v32
	v_mul_f32_e32 v37, 0xbfb8aa3b, v33
	v_mul_f32_e32 v38, 0xbfb8aa3b, v34
	v_mul_f32_e32 v39, 0xbfb8aa3b, v35
	v_exp_f32_e32 v36, v36
	v_exp_f32_e32 v37, v37
	v_exp_f32_e32 v38, v38
	v_exp_f32_e32 v39, v39
	v_pk_mul_f32 v[42:43], v[42:43], v[6:7] op_sel_hi:[1,0]
	v_pk_mul_f32 v[46:47], v[46:47], v[6:7] op_sel_hi:[1,0]
	v_pk_add_f32 v[36:37], v[36:37], 1.0 op_sel_hi:[1,0]
	v_pk_add_f32 v[38:39], v[38:39], 1.0 op_sel_hi:[1,0]
	v_pk_mul_f32 v[42:43], v[204:205], v[42:43]
	v_pk_mul_f32 v[46:47], v[206:207], v[46:47]
	v_rcp_f32_e32 v36, v36
	v_rcp_f32_e32 v37, v37
	v_rcp_f32_e32 v38, v38
	v_rcp_f32_e32 v39, v39
	v_pk_mul_f32 v[32:33], v[32:33], v[36:37]
	v_pk_mul_f32 v[34:35], v[34:35], v[38:39]
	v_pk_mul_f32 v[42:43], v[32:33], v[42:43]
	v_pk_mul_f32 v[46:47], v[34:35], v[46:47]
	v_cvt_pk_bf16_f32 v26, v42, v43
	v_cvt_pk_bf16_f32 v27, v46, v47
	s_nop 1
	v_permlane32_swap_b32_e32 v24, v26
	v_permlane32_swap_b32_e32 v25, v27
	s_nop 0
	v_permlane16_swap_b32_e32 v24, v26
	v_permlane16_swap_b32_e32 v25, v27
	global_store_dwordx4 v[180:181], v[24:27], off
	v_lshlrev_b32_e32 v172, 16, v188
	v_and_b32_e32 v173, 0xffff0000, v188
	v_lshlrev_b32_e32 v174, 16, v189
	v_and_b32_e32 v175, 0xffff0000, v189
	v_mul_f32_e32 v176, 0xbfb8aa3b, v172
	v_mul_f32_e32 v177, 0xbfb8aa3b, v173
	v_mul_f32_e32 v178, 0xbfb8aa3b, v174
	v_mul_f32_e32 v179, 0xbfb8aa3b, v175
	v_exp_f32_e32 v176, v176
	v_exp_f32_e32 v177, v177
	v_exp_f32_e32 v178, v178
	v_exp_f32_e32 v179, v179
	v_pk_mul_f32 v[84:85], v[84:85], v[6:7] op_sel_hi:[1,0]
	v_pk_mul_f32 v[88:89], v[88:89], v[6:7] op_sel_hi:[1,0]
	v_pk_add_f32 v[176:177], v[176:177], 1.0 op_sel_hi:[1,0]
	v_pk_add_f32 v[178:179], v[178:179], 1.0 op_sel_hi:[1,0]
	v_pk_mul_f32 v[84:85], v[208:209], v[84:85]
	v_pk_mul_f32 v[88:89], v[210:211], v[88:89]
	v_rcp_f32_e32 v176, v176
	v_rcp_f32_e32 v177, v177
	v_rcp_f32_e32 v178, v178
	v_rcp_f32_e32 v179, v179
	v_pk_mul_f32 v[172:173], v[172:173], v[176:177]
	v_pk_mul_f32 v[174:175], v[174:175], v[178:179]
	v_pk_mul_f32 v[84:85], v[172:173], v[84:85]
	v_pk_mul_f32 v[88:89], v[174:175], v[88:89]
	v_cvt_pk_bf16_f32 v160, v84, v85
	v_cvt_pk_bf16_f32 v161, v88, v89
	v_lshlrev_b32_e32 v32, 16, v190
	v_and_b32_e32 v33, 0xffff0000, v190
	v_lshlrev_b32_e32 v34, 16, v191
	v_and_b32_e32 v35, 0xffff0000, v191
	v_mul_f32_e32 v36, 0xbfb8aa3b, v32
	v_mul_f32_e32 v37, 0xbfb8aa3b, v33
	v_mul_f32_e32 v38, 0xbfb8aa3b, v34
	v_mul_f32_e32 v39, 0xbfb8aa3b, v35
	v_exp_f32_e32 v36, v36
	v_exp_f32_e32 v37, v37
	v_exp_f32_e32 v38, v38
	v_exp_f32_e32 v39, v39
	v_pk_mul_f32 v[22:23], v[22:23], v[6:7] op_sel_hi:[1,0]
	v_pk_mul_f32 v[20:21], v[20:21], v[6:7] op_sel_hi:[1,0]
	v_pk_add_f32 v[36:37], v[36:37], 1.0 op_sel_hi:[1,0]
	v_pk_add_f32 v[38:39], v[38:39], 1.0 op_sel_hi:[1,0]
	v_pk_mul_f32 v[22:23], v[212:213], v[22:23]
	v_pk_mul_f32 v[20:21], v[214:215], v[20:21]
	v_rcp_f32_e32 v36, v36
	v_rcp_f32_e32 v37, v37
	v_rcp_f32_e32 v38, v38
	v_rcp_f32_e32 v39, v39
	v_pk_mul_f32 v[32:33], v[32:33], v[36:37]
	v_pk_mul_f32 v[34:35], v[34:35], v[38:39]
	v_pk_mul_f32 v[22:23], v[32:33], v[22:23]
	v_pk_mul_f32 v[20:21], v[34:35], v[20:21]
	v_cvt_pk_bf16_f32 v162, v22, v23
	v_cvt_pk_bf16_f32 v163, v20, v21
	s_nop 1
	v_permlane32_swap_b32_e32 v160, v162
	v_permlane32_swap_b32_e32 v161, v163
	s_nop 0
	v_permlane16_swap_b32_e32 v160, v162
	v_permlane16_swap_b32_e32 v161, v163
	global_store_dwordx4 v[180:181], v[160:163], off offset:64
	v_lshlrev_b32_e32 v172, 16, v192
	v_and_b32_e32 v173, 0xffff0000, v192
	v_lshlrev_b32_e32 v174, 16, v193
	v_and_b32_e32 v175, 0xffff0000, v193
	v_mul_f32_e32 v176, 0xbfb8aa3b, v172
	v_mul_f32_e32 v177, 0xbfb8aa3b, v173
	v_mul_f32_e32 v178, 0xbfb8aa3b, v174
	v_mul_f32_e32 v179, 0xbfb8aa3b, v175
	v_exp_f32_e32 v176, v176
	v_exp_f32_e32 v177, v177
	v_exp_f32_e32 v178, v178
	v_exp_f32_e32 v179, v179
	v_pk_mul_f32 v[18:19], v[18:19], v[6:7] op_sel_hi:[1,0]
	v_pk_mul_f32 v[16:17], v[16:17], v[6:7] op_sel_hi:[1,0]
	v_pk_add_f32 v[176:177], v[176:177], 1.0 op_sel_hi:[1,0]
	v_pk_add_f32 v[178:179], v[178:179], 1.0 op_sel_hi:[1,0]
	v_pk_mul_f32 v[18:19], v[216:217], v[18:19]
	v_pk_mul_f32 v[16:17], v[218:219], v[16:17]
	v_rcp_f32_e32 v176, v176
	v_rcp_f32_e32 v177, v177
	v_rcp_f32_e32 v178, v178
	v_rcp_f32_e32 v179, v179
	v_pk_mul_f32 v[172:173], v[172:173], v[176:177]
	v_pk_mul_f32 v[174:175], v[174:175], v[178:179]
	v_pk_mul_f32 v[18:19], v[172:173], v[18:19]
	v_pk_mul_f32 v[16:17], v[174:175], v[16:17]
	v_cvt_pk_bf16_f32 v164, v18, v19
	v_cvt_pk_bf16_f32 v165, v16, v17
	v_lshlrev_b32_e32 v32, 16, v194
	v_and_b32_e32 v33, 0xffff0000, v194
	v_lshlrev_b32_e32 v34, 16, v195
	v_and_b32_e32 v35, 0xffff0000, v195
	v_mul_f32_e32 v36, 0xbfb8aa3b, v32
	v_mul_f32_e32 v37, 0xbfb8aa3b, v33
	v_mul_f32_e32 v38, 0xbfb8aa3b, v34
	v_mul_f32_e32 v39, 0xbfb8aa3b, v35
	v_exp_f32_e32 v36, v36
	v_exp_f32_e32 v37, v37
	v_exp_f32_e32 v38, v38
	v_exp_f32_e32 v39, v39
	v_pk_mul_f32 v[14:15], v[14:15], v[6:7] op_sel_hi:[1,0]
	v_pk_mul_f32 v[12:13], v[12:13], v[6:7] op_sel_hi:[1,0]
	v_pk_add_f32 v[36:37], v[36:37], 1.0 op_sel_hi:[1,0]
	v_pk_add_f32 v[38:39], v[38:39], 1.0 op_sel_hi:[1,0]
	v_pk_mul_f32 v[14:15], v[220:221], v[14:15]
	v_pk_mul_f32 v[12:13], v[222:223], v[12:13]
	v_rcp_f32_e32 v36, v36
	v_rcp_f32_e32 v37, v37
	v_rcp_f32_e32 v38, v38
	v_rcp_f32_e32 v39, v39
	v_pk_mul_f32 v[32:33], v[32:33], v[36:37]
	v_pk_mul_f32 v[34:35], v[34:35], v[38:39]
	v_pk_mul_f32 v[14:15], v[32:33], v[14:15]
	v_pk_mul_f32 v[12:13], v[34:35], v[12:13]
	v_cvt_pk_bf16_f32 v166, v14, v15
	v_cvt_pk_bf16_f32 v167, v12, v13
	s_nop 1
	v_permlane32_swap_b32_e32 v164, v166
	v_permlane32_swap_b32_e32 v165, v167
	s_nop 0
	v_permlane16_swap_b32_e32 v164, v166
	v_permlane16_swap_b32_e32 v165, v167
	global_store_dwordx4 v[180:181], v[164:167], off offset:128
	v_lshlrev_b32_e32 v172, 16, v196
	v_and_b32_e32 v173, 0xffff0000, v196
	v_lshlrev_b32_e32 v174, 16, v197
	v_and_b32_e32 v175, 0xffff0000, v197
	v_mul_f32_e32 v176, 0xbfb8aa3b, v172
	v_mul_f32_e32 v177, 0xbfb8aa3b, v173
	v_mul_f32_e32 v178, 0xbfb8aa3b, v174
	v_mul_f32_e32 v179, 0xbfb8aa3b, v175
	v_exp_f32_e32 v176, v176
	v_exp_f32_e32 v177, v177
	v_exp_f32_e32 v178, v178
	v_exp_f32_e32 v179, v179
	v_pk_mul_f32 v[10:11], v[10:11], v[6:7] op_sel_hi:[1,0]
	v_pk_mul_f32 v[8:9], v[8:9], v[6:7] op_sel_hi:[1,0]
	v_pk_add_f32 v[176:177], v[176:177], 1.0 op_sel_hi:[1,0]
	v_pk_add_f32 v[178:179], v[178:179], 1.0 op_sel_hi:[1,0]
	v_pk_mul_f32 v[10:11], v[224:225], v[10:11]
	v_pk_mul_f32 v[8:9], v[226:227], v[8:9]
	v_rcp_f32_e32 v176, v176
	v_rcp_f32_e32 v177, v177
	v_rcp_f32_e32 v178, v178
	v_rcp_f32_e32 v179, v179
	v_pk_mul_f32 v[172:173], v[172:173], v[176:177]
	v_pk_mul_f32 v[174:175], v[174:175], v[178:179]
	v_pk_mul_f32 v[10:11], v[172:173], v[10:11]
	v_pk_mul_f32 v[8:9], v[174:175], v[8:9]
	v_cvt_pk_bf16_f32 v168, v10, v11
	v_cvt_pk_bf16_f32 v169, v8, v9
	v_lshlrev_b32_e32 v32, 16, v198
	v_and_b32_e32 v33, 0xffff0000, v198
	v_lshlrev_b32_e32 v34, 16, v199
	v_and_b32_e32 v35, 0xffff0000, v199
	v_mul_f32_e32 v36, 0xbfb8aa3b, v32
	v_mul_f32_e32 v37, 0xbfb8aa3b, v33
	v_mul_f32_e32 v38, 0xbfb8aa3b, v34
	v_mul_f32_e32 v39, 0xbfb8aa3b, v35
	v_exp_f32_e32 v36, v36
	v_exp_f32_e32 v37, v37
	v_exp_f32_e32 v38, v38
	v_exp_f32_e32 v39, v39
	v_pk_mul_f32 v[4:5], v[4:5], v[6:7] op_sel_hi:[1,0]
	v_pk_mul_f32 v[0:1], v[0:1], v[6:7] op_sel_hi:[1,0]
	v_pk_add_f32 v[36:37], v[36:37], 1.0 op_sel_hi:[1,0]
	v_pk_add_f32 v[38:39], v[38:39], 1.0 op_sel_hi:[1,0]
	v_pk_mul_f32 v[4:5], v[228:229], v[4:5]
	v_pk_mul_f32 v[0:1], v[230:231], v[0:1]
	v_rcp_f32_e32 v36, v36
	v_rcp_f32_e32 v37, v37
	v_rcp_f32_e32 v38, v38
	v_rcp_f32_e32 v39, v39
	v_pk_mul_f32 v[32:33], v[32:33], v[36:37]
	v_pk_mul_f32 v[34:35], v[34:35], v[38:39]
	v_pk_mul_f32 v[4:5], v[32:33], v[4:5]
	v_pk_mul_f32 v[0:1], v[34:35], v[0:1]
	v_cvt_pk_bf16_f32 v170, v4, v5
	v_cvt_pk_bf16_f32 v171, v0, v1
	s_nop 1
	v_permlane32_swap_b32_e32 v168, v170
	v_permlane32_swap_b32_e32 v169, v171
	s_nop 0
	v_permlane16_swap_b32_e32 v168, v170
	v_permlane16_swap_b32_e32 v169, v171
	global_store_dwordx4 v[180:181], v[168:171], off offset:192
	s_waitcnt lgkmcnt(0)
	s_barrier
	s_cbranch_scc1 .LBB0_495
